# v54 + FFN-down tile order: XCD pairs share the same 4 A row panels per round (column halves split between the two XCDs), so each A panel leaves HBM once; per-XCD-round 4A+8B panels unchanged
# speedup vs baseline: 1.0089x; 1.0089x over previous
;     __device__ __forceinline__ const char* a_tile(const Unit& u) const { return (const char*)A + (size_t)u.pm * 256 * lda2; }
;     __device__ __forceinline__ const char* b_tile(const Unit& u) const { return (const char*)Bt + (size_t)u.pn * 256 * ldb2; }
;     __device__ __forceinline__ size_t a_koff(int t) const { return (size_t)t * 128; }
;     __device__ __forceinline__ const char* a_tile(const Unit& u) const { return (const char*)A + (size_t)u.pm * (size_t)(K / 64) * 32768; }
;     __device__ __forceinline__ const char* b_tile(const Unit& u) const { return (const char*)Bt + (size_t)u.pn * 256 * ldb2; }
;     __device__ __forceinline__ size_t a_koff(int t) const { return (size_t)t * 32768; }
;     __device__ bool next(int i, Unit& u) const { const int L = i * G + c; if (L >= n) return false; u.pm = L; u.pn = 0; return true; }
;     __device__ bool next(int i, Unit& u) const { if (i >= cnt) return false; const int L = start + i; u.pm = L / nN; u.pn = L - u.pm * nN; return true; }
; #define PG8_STAGE(bufoff, gbase, voff) do { _Pragma("unroll") for (int _i = 0; _i < 2; ++_i) \
;         __builtin_amdgcn_global_load_lds((const unsigned*)((const char*)(gbase) + (size_t)_i * p##voff + (voff)), (LAS unsigned*)(lds + (bufoff) + ldsw + _i * 8192), 16, 0, 0); } while (0)
; #define PG8_BAR __builtin_amdgcn_s_barrier()
;     __device__ __forceinline__ const char* b_tile(const Unit& u) const { return (const char*)((u.pm >> 4) ? V1T : K1T); }
;     __device__ __forceinline__ size_t a_koff(int t) const { return (size_t)t * 128; }
;     __device__ bool next(int i, Unit& u) const {
;         const long L = (long)i * G + c; if (L >= nwg) return false;
;         int wgid = (int)L; { const int q = nwg / NXCD, r = nwg % NXCD, xcd = wgid % NXCD, off = wgid / NXCD; wgid = (xcd < r ? xcd * (q + 1) : r * (q + 1) + (xcd - r) * q) + off; }
;         const int nig = wgm * nN, gid = wgid / nig, fm = gid * wgm, gsz = (nM - fm) < wgm ? (nM - fm) : wgm;
;         u.pm = fm + ((wgid % nig) % gsz); u.pn = (wgid % nig) / gsz; return true;
;     ...
;     const char* cA = g.a_tile(cur); const char* cB = g.b_tile(cur);
;     {
;         const char* cA1 = cA + g.a_koff(1);
;         PG8_STAGE(PG8_SB(0, 0), cB, voffB); PG8_STAGE(PG8_SB(0, 1), cB + hstepB, voffB); PG8_STAGE(PG8_SA(0, 0), cA, voffA); PG8_STAGE(PG8_SA(0, 1), cA + hstepA, voffA);
;         if (wr == 1) PG8_BAR;
.LBB0_1271:
	s_add_u32 s52, s30, 0x1fa00000
	s_addc_u32 s53, s31, 0
	s_add_u32 s54, s30, 0xfa00000
	s_addc_u32 s55, s31, 0
	s_lshr_b32 s6, s5, 1
	s_lshl_b32 s6, s6, 8
	s_and_b32 s4, s5, 1
	s_lshl_b32 s4, s4, 5
	s_or_b32 s4, s4, s6
	s_andn2_b32 s6, s2, 31
	s_add_i32 s4, s4, s6
	s_add_i32 s2, s4, s2
	s_ashr_i32 s4, s2, 31
	s_lshr_b32 s4, s4, 26
	s_add_i32 s4, s2, s4
	s_ashr_i32 s5, s4, 6
	s_and_b32 s4, s4, 0xffc0
	s_sub_i32 s4, s2, s4
	s_bfe_i32 s2, s4, 0x80000
	s_bfe_u32 s2, s2, 0x2000d
	s_add_i32 s6, s4, s2
	s_bfe_i32 s2, s6, 0x80000
	s_and_b32 s6, s6, 0xfc
	s_sub_i32 s4, s4, s6
	s_lshl_b32 s5, s5, 2
	s_sext_i32_i16 s2, s2
	s_sext_i32_i8 s4, s4
	s_lshr_b32 s3, s29, 6
	s_lshr_b32 s2, s2, 2
	s_add_i32 s42, s5, s4
	s_ashr_i32 s43, s42, 31
	s_bfe_i64 s[4:5], s[2:3], 0x100000
	s_lshr_b32 s28, s29, 8
	v_lshlrev_b32_e32 v1, 4, v0
	s_waitcnt vmcnt(0)
	v_and_b32_e32 v2, 32, v0
	v_lshrrev_b32_e32 v3, 3, v0
	v_bfe_u32 v6, v0, 2, 4
	s_waitcnt lgkmcnt(0)
	v_lshrrev_b32_e32 v5, 1, v0
	v_lshrrev_b32_e32 v9, 5, v0
	v_bfe_u32 v10, v0, 2, 2
	s_lshl_b32 s56, s3, 10
	s_lshl_b64 s[6:7], s[42:43], 23
	s_lshl_b64 s[4:5], s[4:5], 23
	v_and_or_b32 v4, v3, 48, v6
	v_bitop3_b32 v7, v1, v2, 48 bitop3:0x6c
	v_and_b32_e32 v8, 64, v0
	v_and_b32_e32 v3, 32, v3
	v_and_b32_e32 v5, 24, v5
	v_and_or_b32 v9, v9, 4, v10
	s_add_u32 s48, s54, s4
	v_or_b32_e32 v2, v7, v8
	v_or3_b32 v3, v9, v3, v5
	s_addc_u32 s49, s55, s5
	s_add_i32 s57, s56, 0
	v_lshl_or_b32 v130, v3, 15, v2
	v_mov_b32_e32 v133, 0
	s_add_i32 m0, s57, 0x10000
	v_mov_b32_e32 v131, v133
	global_load_lds_dwordx4 v130, s[48:49]
	s_add_i32 m0, s57, 0x12000
	v_lshl_or_b32 v128, v4, 7, v2
	v_lshl_add_u64 v[2:3], s[48:49], 0, v[130:131]
	s_mov_b64 s[4:5], 0x200000
	s_add_u32 s44, s52, s6
	v_lshl_add_u64 v[4:5], v[2:3], 0, s[4:5]
	s_addc_u32 s45, s53, s7
	s_mov_b64 s[6:7], 0x400000
	global_load_lds_dwordx4 v[4:5], off
	v_lshl_add_u64 v[4:5], v[2:3], 0, s[6:7]
	s_add_i32 m0, s57, 0x14000
	s_mov_b64 s[8:9], 0x600000
	global_load_lds_dwordx4 v[4:5], off
	v_lshl_add_u64 v[4:5], v[2:3], 0, s[8:9]
	s_add_i32 m0, s57, 0x16000
	v_mov_b32_e32 v129, v133
	global_load_lds_dwordx4 v[4:5], off
	v_lshl_add_u64 v[4:5], s[44:45], 0, v[128:129]
	s_mov_b32 m0, s57
	s_mov_b64 s[10:11], 0x2000
	s_add_i32 s58, s57, 0x2000
	global_load_lds_dwordx4 v128, s[44:45]
	v_lshl_add_u64 v[10:11], v[4:5], 0, s[10:11]
	s_mov_b32 m0, s58
	s_mov_b64 s[12:13], 0x4000
	s_add_i32 s59, s57, 0x4000
	global_load_lds_dwordx4 v[10:11], off
	v_lshl_add_u64 v[10:11], v[4:5], 0, s[12:13]
	s_mov_b32 m0, s59
	s_mov_b64 s[14:15], 0x6000
	s_add_i32 s60, s57, 0x6000
	global_load_lds_dwordx4 v[10:11], off
	v_lshl_add_u64 v[10:11], v[4:5], 0, s[14:15]
	s_mov_b32 m0, s60
	s_mov_b32 s61, 0
	global_load_lds_dwordx4 v[10:11], off
	s_mov_b32 s62, 0x10000
	s_mov_b32 s63, 0x12000
	s_mov_b32 s64, 0x14000
	s_mov_b32 s65, 0x16000
	s_movk_i32 s66, 0x2000
	s_movk_i32 s67, 0x4000
	s_cmp_lg_u32 s28, 1
	s_movk_i32 s68, 0x6000
	s_cbranch_scc1 .LBB0_1273
	s_barrier

;     __device__ bool next(int i, Unit& u) const { const int L = i * G + c; if (L >= n) return false; u.pm = L; u.pn = 0; return true; }
;     __device__ bool next(int i, Unit& u) const { if (i >= cnt) return false; const int L = start + i; u.pm = L / nN; u.pn = L - u.pm * nN; return true; }
;     __device__ bool next(int i, Unit& u) const {
;         const long L = (long)i * G + c; if (L >= nwg) return false;
;         int wgid = (int)L; { const int q = nwg / NXCD, r = nwg % NXCD, xcd = wgid % NXCD, off = wgid / NXCD; wgid = (xcd < r ? xcd * (q + 1) : r * (q + 1) + (xcd - r) * q) + off; }
;         const int nig = wgm * nN, gid = wgid / nig, fm = gid * wgm, gsz = (nM - fm) < wgm ? (nM - fm) : wgm;
;         u.pm = fm + ((wgid % nig) % gsz); u.pn = (wgid % nig) / gsz; return true;
.LBB0_1279:
	s_ashr_i32 s34, s36, 3
	s_lshr_b32 s40, s37, 1
	s_lshl_b32 s40, s40, 8
	s_and_b32 s35, s37, 1
	s_lshl_b32 s35, s35, 5
	s_or_b32 s40, s40, s35
	s_andn2_b32 s35, s34, 31
	s_add_i32 s40, s40, s35
	s_add_i32 s34, s40, s34
	s_ashr_i32 s35, s34, 31
	s_lshr_b32 s35, s35, 26
	s_add_i32 s35, s34, s35
	s_ashr_i32 s36, s35, 6
	s_lshl_b32 s36, s36, 2
	s_sub_i32 s37, 64, s36
	s_min_i32 s37, s37, 4
	s_abs_i32 s40, s37
	v_cvt_f32_u32_e32 v0, s40
	s_sub_i32 s43, 0, s40
	s_andn2_b32 s35, s35, 63
	s_sub_i32 s35, s34, s35
	v_rcp_iflag_f32_e32 v0, v0
	s_abs_i32 s34, s35
	s_xor_b32 s41, s35, s37
	s_ashr_i32 s41, s41, 31
	v_mul_f32_e32 v0, 0x4f7ffffe, v0
	v_cvt_u32_f32_e32 v0, v0
	s_nop 0
	v_readfirstlane_b32 s47, v0
	s_mul_i32 s43, s43, s47
	s_mul_hi_u32 s43, s47, s43
	s_add_i32 s47, s47, s43
	s_mul_hi_u32 s43, s34, s47
	s_mul_i32 s47, s43, s40
	s_sub_i32 s34, s34, s47
	s_add_i32 s50, s43, 1
	s_sub_i32 s47, s34, s40
	s_cmp_ge_u32 s34, s40
	s_cselect_b32 s43, s50, s43
	s_cselect_b32 s34, s47, s34
	s_add_i32 s47, s43, 1
	s_cmp_ge_u32 s34, s40
	s_cselect_b32 s34, s47, s43
	s_xor_b32 s34, s34, s41
	s_sub_i32 s34, s34, s41
	s_mul_i32 s37, s34, s37
	s_sub_i32 s35, s35, s37
	s_add_i32 s36, s36, s35
